# adds: mixA unit schedule rebalanced (blocks owning swa_sample units hand three swa_prompt units to the other blocks)
# speedup vs baseline: 1.0092x; 1.0092x over previous
; __device__ __forceinline__ void swa_prompt_unit(const Ctx& P, int li, int b, int qh, int n, LAS unsigned char* lds, const bf16_t* PROJ, bf16_t* H, int tid) {
;     ...
;     for (int r = 0; r < 4; ++r) { const int idx = tid + 512 * r, jj = idx & 255, seg = idx >> 8;
;         const bool valid = (n > 0) || (jj >= 128);
;         u32x4 kv = {0u, 0u, 0u, 0u}, vv = {0u, 0u, 0u, 0u};
;         if (valid) { const bf16_t* rp = PROJ + (size_t)(R0 - 128 + jj) * EIN + kvh * 64 + seg * 8; kv = *(const u32x4*)(rp + 5120); vv = *(const u32x4*)(rp + 5248); }
; __device__ __forceinline__ void phase_even_mixA(const Ctx& P, int li, LAS unsigned char* lds) {
;     ...
;     for (int u = P.bid; u < 1856; u += P.nb) {
;         int tid = P.tid; asm volatile("" : "+v"(tid));
;     ...
;         if (u < 1024) { const int n = u & 31, qh = (u >> 5) & 15, b = u >> 9; swa_prompt_unit(P, li, b, qh, n, lds, PROJ, H, tid); }
.LBB0_444:
	s_add_i32 s31, s31, s2
	s_sub_i32 s26, s26, s27
	s_mov_b32 s38, s31
	s_cmpk_gt_i32 s31, 0x73f
	s_cbranch_scc0 .LBB0_445
	s_cmpk_gt_i32 s31, 0x7ff
	s_cbranch_scc1 .LBB0_502
	s_sub_i32 s38, s30, 64
	s_lshr_b32 s98, s38, 6
	s_and_b32 s38, s38, 63
	s_add_i32 s98, s98, 1
	s_lshl_b32 s98, s98, 8
	s_add_i32 s38, s38, s98
.LBB0_445:
	v_mov_b32_e32 v47, v179
	s_cmpk_gt_u32 s30, 63
	s_cbranch_scc1 .Lmix_go
	s_cmpk_lt_i32 s38, 0x100
	s_cbranch_scc1 .Lmix_go
	s_cmpk_gt_i32 s38, 0x3ff
	s_cbranch_scc0 .LBB0_444
.Lmix_go:
	s_cmpk_gt_i32 s38, 0x3ff
	s_cbranch_scc1 .LBB0_469
	s_ashr_i32 s0, s38, 9
	s_and_b32 s4, s38, 31
	s_ashr_i32 s1, s0, 31
	s_lshl_b64 s[0:1], s[0:1], 12
	s_lshl_b32 s5, s4, 7
	s_or_b32 s0, s0, s5
	v_and_b32_e32 v128, 0xff, v47
	s_movk_i32 s20, 0xff80
	v_lshl_add_u64 v[0:1], v[128:129], 0, s[0:1]
	s_mov_b32 s21, -1
	v_lshl_add_u64 v[0:1], v[0:1], 0, s[20:21]
	v_mov_b64_e32 v[2:3], s[14:15]
	s_cmp_lg_u32 s4, 0
	v_mad_u64_u32 v[2:3], s[20:21], v0, s35, v[2:3]
	s_cselect_b64 s[4:5], -1, 0
	s_movk_i32 s18, 0x7f
	s_lshr_b32 s20, s38, 1
	v_cmp_lt_u32_e32 vcc, s18, v128
	v_mad_i32_i24 v3, v1, s35, v3
	s_and_b32 s24, s20, 0x80
	s_waitcnt vmcnt(10)
	v_mov_b32_e32 v6, 0
	s_or_b64 s[18:19], s[4:5], vcc
	s_waitcnt vmcnt(9)
	v_lshl_add_u64 v[10:11], v[2:3], 0, s[24:25]
	v_ashrrev_i32_e32 v1, 8, v47
	v_mov_b32_e32 v0, 0
	v_mov_b32_e32 v2, 0
	v_mov_b32_e32 v3, 0
	v_mov_b32_e32 v4, 0
	v_mov_b32_e32 v5, 0
	v_mov_b32_e32 v7, v6
	v_mov_b32_e32 v8, v6
	v_mov_b32_e32 v9, v6
	s_and_saveexec_b64 s[20:21], s[18:19]
	s_cbranch_execz .LBB0_448
	v_lshlrev_b32_e32 v2, 3, v1
	v_ashrrev_i32_e32 v3, 31, v2
	v_lshl_add_u64 v[2:3], v[2:3], 1, v[10:11]
	v_add_co_u32_e32 v2, vcc, 0x2000, v2
	s_nop 1
	v_addc_co_u32_e32 v3, vcc, 0, v3, vcc
	global_load_dwordx4 v[6:9], v[2:3], off offset:2048
	s_nop 0
	global_load_dwordx4 v[2:5], v[2:3], off offset:2304
